# P3: first W1 slab waited for at its LDS write; W2 fragments requested at the start of the activation stage
# baseline (speedup 1.0000x reference)
.LBB0_484:
	s_ashr_i32 s22, s21, 3
	s_and_b32 s23, s21, 1
	s_ashr_i32 s10, s21, 4
	s_and_b32 s0, s22, 1
	s_cmp_eq_u32 s23, 0
	s_cselect_b64 s[8:9], -1, 0
	s_and_b64 s[12:13], s[8:9], exec
	s_cselect_b32 s11, 28, 30
	s_or_b32 s12, s0, s11
	s_ashr_i32 s11, s10, 31
	v_and_or_b32 v2, s21, 6, v1
	s_lshl_b64 s[10:11], s[10:11], 19
	s_add_u32 s13, s15, s10
	v_lshlrev_b32_e32 v126, 5, v2
	s_addc_u32 s24, s16, s11
	s_lshl_b32 s0, s23, 20
	v_or_b32_e32 v2, v126, v74
	v_lshlrev_b32_e32 v3, 10, v2
	v_cmp_ne_u32_e32 vcc, s14, v2
	v_lshl_add_u64 v[4:5], v[78:79], 0, s[0:1]
	s_lshl_b32 s25, s12, 23
	v_cndmask_b32_e32 v2, v124, v3, vcc
	v_add_co_u32_e32 v6, vcc, s18, v4
	global_load_dwordx4 v[26:29], v[4:5], off
	s_nop 0
	v_addc_co_u32_e32 v7, vcc, 0, v5, vcc
	v_add_co_u32_e32 v8, vcc, s19, v4
	global_load_dwordx4 v[30:33], v[6:7], off
	s_nop 0
	v_addc_co_u32_e32 v9, vcc, 0, v5, vcc
	v_add_co_u32_e32 v10, vcc, s20, v4
	global_load_dwordx4 v[50:53], v[8:9], off
	s_nop 0
	v_addc_co_u32_e32 v11, vcc, 0, v5, vcc
	global_load_dwordx4 v[54:57], v[10:11], off
	s_add_u32 s12, s13, s25
	s_addc_u32 s13, s24, 0
	v_lshlrev_b32_e32 v34, 1, v2
	v_mov_b32_e32 v35, v77
	v_lshl_add_u64 v[2:3], s[12:13], 0, v[34:35]
	v_lshl_add_u64 v[2:3], v[2:3], 0, v[76:77]
	global_load_dwordx4 v[66:69], v[2:3], off
	global_load_dwordx4 v[42:45], v[4:5], off offset:128
	global_load_dwordx4 v[46:49], v[6:7], off offset:128
	global_load_dwordx4 v[58:61], v[8:9], off offset:128
	global_load_dwordx4 v[62:65], v[10:11], off offset:128
	global_load_dwordx4 v[70:73], v[2:3], off offset:128
	s_add_u32 s10, s25, s10
	s_addc_u32 s11, 0, s11
	v_cndmask_b32_e64 v36, 0, 1, s[2:3]
	s_add_u32 s10, s96, s10
	v_mov_b32_e32 v37, v77
	v_lshlrev_b32_e32 v36, 20, v36
	s_addc_u32 s11, s97, s11
	v_add_u32_e32 v91, v101, v100
	s_mov_b32 s0, -2
	v_mov_b32_e32 v2, 0
	v_mov_b32_e32 v3, v77
	v_mov_b32_e32 v4, v77
	v_mov_b32_e32 v5, v77
	v_mov_b32_e32 v6, 0
	v_mov_b32_e32 v7, v77
	v_mov_b32_e32 v8, v77
	v_mov_b32_e32 v9, v77
	v_mov_b32_e32 v10, 0
	v_mov_b32_e32 v11, v77
	v_mov_b32_e32 v12, v77
	v_mov_b32_e32 v13, v77
	v_mov_b32_e32 v14, 0
	v_mov_b32_e32 v15, v77
	v_mov_b32_e32 v16, v77
	v_mov_b32_e32 v17, v77
	v_mov_b32_e32 v18, 0
	v_mov_b32_e32 v19, v77
	v_mov_b32_e32 v20, v77
	v_mov_b32_e32 v21, v77
	v_mov_b32_e32 v22, 0
	v_mov_b32_e32 v23, v77
	v_mov_b32_e32 v24, v77
	v_mov_b32_e32 v25, v77
	v_mov_b32_e32 v90, s22
	v_lshl_add_u64 v[92:93], v[88:89], 0, v[36:37]
	v_lshl_add_u64 v[94:95], s[10:11], 0, v[34:35]
	v_mov_b32_e32 v34, 0
	v_mov_b32_e32 v36, v77
	v_mov_b32_e32 v38, 0
	v_mov_b32_e32 v39, v77
	v_mov_b32_e32 v40, v77
	v_mov_b32_e32 v41, v77
	s_waitcnt vmcnt(6)
	ds_write_b128 v75, v[26:29]
	ds_write_b128 v75, v[30:33] offset:8192
	ds_write_b128 v75, v[50:53] offset:16384
	ds_write_b128 v75, v[54:57] offset:24576
	s_waitcnt vmcnt(5)
	ds_write_b128 v91, v[66:69] offset:32768
	s_waitcnt lgkmcnt(0)
	s_barrier
	s_branch .LBB0_486

.LBB0_492:
	s_lshl_b32 s10, s23, 10
	s_mov_b32 s11, s1
	v_lshl_add_u64 v[50:51], v[84:85], 0, s[10:11]
	global_load_dwordx4 v[26:29], v[50:51], off
	global_load_dwordx4 v[30:33], v[50:51], off offset:64
	global_load_dwordx4 v[42:45], v[50:51], off offset:128
	global_load_dwordx4 v[46:49], v[50:51], off offset:192
	s_lshl_b32 s0, s23, 15
	v_lshl_add_u64 v[160:161], v[80:81], 0, s[0:1]
	global_load_dwordx4 v[128:131], v[160:161], off
	global_load_dwordx4 v[132:135], v[160:161], off offset:64
	global_load_dwordx4 v[136:139], v[160:161], off offset:128
	global_load_dwordx4 v[140:143], v[160:161], off offset:192
	global_load_dwordx4 v[144:147], v[160:161], off offset:256
	global_load_dwordx4 v[148:151], v[160:161], off offset:320
	global_load_dwordx4 v[152:155], v[160:161], off offset:384
	global_load_dwordx4 v[156:159], v[160:161], off offset:448
	s_mov_b64 s[10:11], 0xf00000
	s_and_b64 vcc, s[8:9], exec
	s_waitcnt vmcnt(11)
	v_pk_add_f32 v[40:41], v[40:41], v[28:29]
	s_waitcnt vmcnt(10)
	v_pk_add_f32 v[20:21], v[20:21], v[32:33]
	v_pk_add_f32 v[18:19], v[18:19], v[30:31]
	v_mul_f32_e32 v56, 0xbfb8aa3b, v20
	v_mul_f32_e32 v54, 0xbfb8aa3b, v18
	v_mul_f32_e32 v55, 0xbfb8aa3b, v19
	v_mul_f32_e32 v57, 0xbfb8aa3b, v21
	v_exp_f32_e32 v54, v54
	v_exp_f32_e32 v55, v55
	v_exp_f32_e32 v56, v56
	v_exp_f32_e32 v57, v57
	v_add_f32_e32 v54, 1.0, v54
	v_add_f32_e32 v55, 1.0, v55
	v_add_f32_e32 v56, 1.0, v56
	v_add_f32_e32 v57, 1.0, v57
	v_rcp_f32_e32 v54, v54
	v_rcp_f32_e32 v55, v55
	v_rcp_f32_e32 v56, v56
	v_rcp_f32_e32 v57, v57
	v_pk_add_f32 v[24:25], v[24:25], v[32:33]
	v_pk_add_f32 v[22:23], v[22:23], v[30:31]
	v_pk_mul_f32 v[18:19], v[18:19], v[54:55]
	v_pk_mul_f32 v[20:21], v[20:21], v[56:57]
	s_waitcnt vmcnt(9)
	v_pk_add_f32 v[14:15], v[14:15], v[42:43]
	v_mul_f32_e32 v50, 0xbfb8aa3b, v22
	v_mul_f32_e32 v51, 0xbfb8aa3b, v23
	v_mul_f32_e32 v52, 0xbfb8aa3b, v24
	v_mul_f32_e32 v53, 0xbfb8aa3b, v25
	v_cvt_pk_bf16_f32 v18, v18, v19
	v_cvt_pk_bf16_f32 v19, v20, v21
	v_mul_f32_e32 v20, 0xbfb8aa3b, v14
	v_mul_f32_e32 v21, 0xbfb8aa3b, v15
	v_exp_f32_e32 v50, v50
	v_exp_f32_e32 v51, v51
	v_exp_f32_e32 v52, v52
	v_exp_f32_e32 v53, v53
	v_exp_f32_e32 v20, v20
	v_exp_f32_e32 v21, v21
	v_add_f32_e32 v50, 1.0, v50
	v_add_f32_e32 v51, 1.0, v51
	v_add_f32_e32 v52, 1.0, v52
	v_add_f32_e32 v53, 1.0, v53
	v_add_f32_e32 v20, 1.0, v20
	v_add_f32_e32 v21, 1.0, v21
	v_rcp_f32_e32 v50, v50
	v_rcp_f32_e32 v51, v51
	v_rcp_f32_e32 v52, v52
	v_rcp_f32_e32 v53, v53
	v_rcp_f32_e32 v20, v20
	v_rcp_f32_e32 v21, v21
	v_pk_mul_f32 v[22:23], v[22:23], v[50:51]
	v_pk_mul_f32 v[24:25], v[24:25], v[52:53]
	v_pk_add_f32 v[10:11], v[10:11], v[42:43]
	v_pk_mul_f32 v[14:15], v[14:15], v[20:21]
	v_cvt_pk_bf16_f32 v22, v22, v23
	v_cvt_pk_bf16_f32 v23, v24, v25
	v_cvt_pk_bf16_f32 v14, v14, v15
	v_mul_f32_e32 v15, 0xbfb8aa3b, v10
	ds_write2st64_b64 v111, v[22:23], v[18:19] offset1:16
	v_exp_f32_e32 v15, v15
	v_mul_f32_e32 v18, 0xbfb8aa3b, v11
	v_exp_f32_e32 v19, v18
	v_pk_add_f32 v[12:13], v[12:13], v[44:45]
	v_add_f32_e32 v15, 1.0, v15
	v_rcp_f32_e32 v18, v15
	v_add_f32_e32 v15, 1.0, v19
	v_mul_f32_e32 v19, 0xbfb8aa3b, v12
	v_exp_f32_e32 v20, v19
	v_mul_f32_e32 v19, 0xbfb8aa3b, v13
	v_exp_f32_e32 v21, v19
	v_rcp_f32_e32 v19, v15
	v_add_f32_e32 v15, 1.0, v20
	v_rcp_f32_e32 v20, v15
	v_add_f32_e32 v15, 1.0, v21
	v_rcp_f32_e32 v21, v15
	v_pk_add_f32 v[16:17], v[16:17], v[44:45]
	v_pk_mul_f32 v[10:11], v[10:11], v[18:19]
	s_waitcnt vmcnt(8)
	v_pk_add_f32 v[6:7], v[6:7], v[46:47]
	v_pk_mul_f32 v[12:13], v[12:13], v[20:21]
	v_mul_f32_e32 v24, 0xbfb8aa3b, v16
	v_mul_f32_e32 v25, 0xbfb8aa3b, v17
	v_cvt_pk_bf16_f32 v10, v10, v11
	v_cvt_pk_bf16_f32 v11, v12, v13
	v_mul_f32_e32 v12, 0xbfb8aa3b, v6
	v_mul_f32_e32 v13, 0xbfb8aa3b, v7
	v_exp_f32_e32 v24, v24
	v_exp_f32_e32 v25, v25
	v_exp_f32_e32 v12, v12
	v_exp_f32_e32 v13, v13
	v_add_f32_e32 v24, 1.0, v24
	v_add_f32_e32 v25, 1.0, v25
	v_add_f32_e32 v12, 1.0, v12
	v_add_f32_e32 v13, 1.0, v13
	v_rcp_f32_e32 v24, v24
	v_rcp_f32_e32 v25, v25
	v_rcp_f32_e32 v12, v12
	v_rcp_f32_e32 v13, v13
	v_pk_add_f32 v[2:3], v[2:3], v[46:47]
	v_pk_mul_f32 v[16:17], v[16:17], v[24:25]
	v_pk_add_f32 v[38:39], v[38:39], v[26:27]
	v_pk_mul_f32 v[6:7], v[6:7], v[12:13]
	v_cvt_pk_bf16_f32 v15, v16, v17
	v_cvt_pk_bf16_f32 v6, v6, v7
	v_mul_f32_e32 v7, 0xbfb8aa3b, v2
	ds_write2st64_b64 v112, v[14:15], v[10:11] offset1:16
	v_exp_f32_e32 v7, v7
	v_mul_f32_e32 v10, 0xbfb8aa3b, v3
	v_exp_f32_e32 v11, v10
	v_pk_add_f32 v[28:29], v[36:37], v[28:29]
	v_pk_add_f32 v[26:27], v[34:35], v[26:27]
	v_pk_add_f32 v[4:5], v[4:5], v[48:49]
	v_add_f32_e32 v7, 1.0, v7
	v_mul_f32_e32 v30, 0xbfb8aa3b, v38
	v_mul_f32_e32 v31, 0xbfb8aa3b, v39
	v_mul_f32_e32 v32, 0xbfb8aa3b, v40
	v_mul_f32_e32 v33, 0xbfb8aa3b, v41
	v_mul_f32_e32 v34, 0xbfb8aa3b, v26
	v_mul_f32_e32 v35, 0xbfb8aa3b, v27
	v_mul_f32_e32 v36, 0xbfb8aa3b, v28
	v_mul_f32_e32 v37, 0xbfb8aa3b, v29
	v_pk_add_f32 v[8:9], v[8:9], v[48:49]
	v_rcp_f32_e32 v10, v7
	v_add_f32_e32 v7, 1.0, v11
	v_mul_f32_e32 v11, 0xbfb8aa3b, v4
	v_exp_f32_e32 v30, v30
	v_exp_f32_e32 v31, v31
	v_exp_f32_e32 v32, v32
	v_exp_f32_e32 v33, v33
	v_exp_f32_e32 v34, v34
	v_exp_f32_e32 v35, v35
	v_exp_f32_e32 v36, v36
	v_exp_f32_e32 v37, v37
	v_mul_f32_e32 v16, 0xbfb8aa3b, v8
	v_mul_f32_e32 v17, 0xbfb8aa3b, v9
	v_exp_f32_e32 v12, v11
	v_mul_f32_e32 v11, 0xbfb8aa3b, v5
	v_exp_f32_e32 v16, v16
	v_exp_f32_e32 v17, v17
	v_exp_f32_e32 v13, v11
	v_add_f32_e32 v30, 1.0, v30
	v_add_f32_e32 v31, 1.0, v31
	v_add_f32_e32 v32, 1.0, v32
	v_add_f32_e32 v33, 1.0, v33
	v_add_f32_e32 v34, 1.0, v34
	v_add_f32_e32 v35, 1.0, v35
	v_add_f32_e32 v36, 1.0, v36
	v_add_f32_e32 v37, 1.0, v37
	v_rcp_f32_e32 v11, v7
	v_add_f32_e32 v7, 1.0, v12
	v_rcp_f32_e32 v30, v30
	v_rcp_f32_e32 v31, v31
	v_rcp_f32_e32 v32, v32
	v_rcp_f32_e32 v33, v33
	v_rcp_f32_e32 v34, v34
	v_rcp_f32_e32 v35, v35
	v_rcp_f32_e32 v36, v36
	v_rcp_f32_e32 v37, v37
	v_add_f32_e32 v16, 1.0, v16
	v_add_f32_e32 v17, 1.0, v17
	v_rcp_f32_e32 v12, v7
	v_add_f32_e32 v7, 1.0, v13
	v_rcp_f32_e32 v16, v16
	v_rcp_f32_e32 v17, v17
	v_rcp_f32_e32 v13, v7
	v_pk_mul_f32 v[30:31], v[38:39], v[30:31]
	v_pk_mul_f32 v[32:33], v[40:41], v[32:33]
	v_pk_mul_f32 v[26:27], v[26:27], v[34:35]
	v_pk_mul_f32 v[28:29], v[28:29], v[36:37]
	v_cvt_pk_bf16_f32 v30, v30, v31
	v_cvt_pk_bf16_f32 v31, v32, v33
	v_cvt_pk_bf16_f32 v26, v26, v27
	v_cvt_pk_bf16_f32 v27, v28, v29
	v_pk_mul_f32 v[8:9], v[8:9], v[16:17]
	v_pk_mul_f32 v[2:3], v[2:3], v[10:11]
	v_pk_mul_f32 v[4:5], v[4:5], v[12:13]
	ds_write2st64_b64 v110, v[30:31], v[26:27] offset1:16
	v_cvt_pk_bf16_f32 v7, v8, v9
	v_cvt_pk_bf16_f32 v2, v2, v3
	v_cvt_pk_bf16_f32 v3, v4, v5
	v_lshl_add_u64 v[26:27], v[80:81], 0, s[0:1]
	ds_write2st64_b64 v113, v[6:7], v[2:3] offset1:16
	s_waitcnt lgkmcnt(0)
	s_barrier
	ds_read_b128 v[10:13], v114
	ds_read_b128 v[14:17], v114 offset:8192
	ds_read_b128 v[18:21], v115
	ds_read_b128 v[22:25], v115 offset:8192
	s_waitcnt vmcnt(0) lgkmcnt(3)
	v_mfma_f32_16x16x32_bf16 v[6:9], v[128:131], v[10:13], 0
	s_waitcnt lgkmcnt(2)
	v_mfma_f32_16x16x32_bf16 v[2:5], v[128:131], v[14:17], 0
	ds_read_b128 v[10:13], v116
	ds_read_b128 v[14:17], v116 offset:8192
	s_waitcnt lgkmcnt(3)
	v_mfma_f32_16x16x32_bf16 v[6:9], v[132:135], v[18:21], v[6:9]
	s_waitcnt lgkmcnt(2)
	v_mfma_f32_16x16x32_bf16 v[2:5], v[132:135], v[22:25], v[2:5]
	ds_read_b128 v[18:21], v117
	ds_read_b128 v[22:25], v117 offset:8192
	s_waitcnt lgkmcnt(3)
	v_mfma_f32_16x16x32_bf16 v[6:9], v[136:139], v[10:13], v[6:9]
	s_waitcnt lgkmcnt(2)
	v_mfma_f32_16x16x32_bf16 v[2:5], v[136:139], v[14:17], v[2:5]
	ds_read_b128 v[10:13], v118
	ds_read_b128 v[14:17], v118 offset:8192
	s_waitcnt lgkmcnt(3)
	v_mfma_f32_16x16x32_bf16 v[6:9], v[140:143], v[18:21], v[6:9]
	s_waitcnt lgkmcnt(2)
	v_mfma_f32_16x16x32_bf16 v[2:5], v[140:143], v[22:25], v[2:5]
	ds_read_b128 v[18:21], v119
	ds_read_b128 v[22:25], v119 offset:8192
	s_waitcnt lgkmcnt(3)
	v_mfma_f32_16x16x32_bf16 v[6:9], v[144:147], v[10:13], v[6:9]
	s_waitcnt lgkmcnt(2)
	v_mfma_f32_16x16x32_bf16 v[2:5], v[144:147], v[14:17], v[2:5]
	ds_read_b128 v[10:13], v120
	ds_read_b128 v[14:17], v120 offset:8192
	s_waitcnt lgkmcnt(3)
	v_mfma_f32_16x16x32_bf16 v[6:9], v[148:151], v[18:21], v[6:9]
	s_waitcnt lgkmcnt(2)
	v_mfma_f32_16x16x32_bf16 v[2:5], v[148:151], v[22:25], v[2:5]
	ds_read_b128 v[18:21], v121
	ds_read_b128 v[22:25], v121 offset:8192
	s_waitcnt lgkmcnt(3)
	v_mfma_f32_16x16x32_bf16 v[6:9], v[152:155], v[10:13], v[6:9]
	s_waitcnt lgkmcnt(2)
	v_mfma_f32_16x16x32_bf16 v[2:5], v[152:155], v[14:17], v[2:5]
	s_waitcnt lgkmcnt(1)
	v_mfma_f32_16x16x32_bf16 v[6:9], v[156:159], v[18:21], v[6:9]
	s_waitcnt lgkmcnt(0)
	v_mfma_f32_16x16x32_bf16 v[2:5], v[156:159], v[22:25], v[2:5]
	s_nop 5
	ds_write_b128 v122, v[6:9] offset:16384
	s_nop 0
	ds_write_b128 v122, v[2:5] offset:20736
	s_waitcnt lgkmcnt(0)
	s_barrier
	ds_read_b128 v[6:9], v109 offset:16384
	ds_read_b128 v[2:5], v109 offset:16400
	s_cbranch_vccz .LBB0_483
	global_load_dwordx4 v[10:13], v[82:83], off
	global_load_dwordx4 v[14:17], v[82:83], off offset:16
	s_waitcnt lgkmcnt(1)
	v_pk_mul_f32 v[18:19], v[8:9], v[8:9]
	v_pk_mul_f32 v[20:21], v[6:7], v[6:7]
	s_waitcnt lgkmcnt(0)
	v_pk_mul_f32 v[22:23], v[4:5], v[4:5]
	v_pk_mul_f32 v[24:25], v[2:3], v[2:3]
	v_and_b32_e32 v29, 64, v125
	v_pk_mov_b32 v[26:27], v[20:21], v[18:19] op_sel:[1,0]
	v_mov_b32_e32 v21, v19
	v_xor_b32_e32 v28, 1, v125
	v_mov_b32_e32 v18, v22
	v_mov_b32_e32 v19, v24
	v_mov_b32_e32 v24, v23
	v_add_u32_e32 v22, 64, v29
	v_pk_add_f32 v[20:21], v[26:27], v[20:21]
	v_pk_add_f32 v[18:19], v[18:19], v[24:25]
	v_cmp_lt_i32_e32 vcc, v28, v22
	v_add_f32_e32 v20, v20, v21
	v_add_f32_e32 v19, v20, v19
	v_cndmask_b32_e32 v23, v125, v28, vcc
	v_lshlrev_b32_e32 v21, 2, v23
	v_add_f32_e32 v18, v18, v19
	ds_bpermute_b32 v19, v21, v18
	v_xor_b32_e32 v20, 2, v125
	v_cmp_lt_i32_e32 vcc, v20, v22
	s_mov_b64 s[10:11], 0xe00000
	s_waitcnt lgkmcnt(0)
	v_add_f32_e32 v18, v18, v19
	v_cndmask_b32_e32 v20, v125, v20, vcc
	v_lshlrev_b32_e32 v20, 2, v20
	ds_bpermute_b32 v19, v20, v18
	v_xor_b32_e32 v20, 4, v125
	v_cmp_lt_i32_e32 vcc, v20, v22
	s_waitcnt lgkmcnt(0)
	v_add_f32_e32 v18, v18, v19
	v_cndmask_b32_e32 v20, v125, v20, vcc
	v_lshlrev_b32_e32 v20, 2, v20
	ds_bpermute_b32 v19, v20, v18
	s_waitcnt lgkmcnt(0)
	v_add_f32_e32 v18, v18, v19
	v_fmamk_f32 v18, v18, 0x3c800000, v123
	v_rsq_f32_e32 v18, v18
	s_nop 0
	v_pk_mul_f32 v[6:7], v[6:7], v[18:19] op_sel_hi:[1,0]
	v_pk_mul_f32 v[8:9], v[8:9], v[18:19] op_sel_hi:[1,0]
	v_pk_mul_f32 v[2:3], v[2:3], v[18:19] op_sel_hi:[1,0]
	v_pk_mul_f32 v[4:5], v[4:5], v[18:19] op_sel_hi:[1,0]
	s_waitcnt vmcnt(1)
	v_pk_mul_f32 v[8:9], v[12:13], v[8:9]
	v_pk_mul_f32 v[6:7], v[10:11], v[6:7]
	s_waitcnt vmcnt(0)
	v_pk_mul_f32 v[4:5], v[16:17], v[4:5]
	v_pk_mul_f32 v[2:3], v[14:15], v[2:3]
	s_branch .LBB0_483
